# Wo GEMM epilogue: residual loads batched 12 at a time with counted vmcnt instead of a 16-step load/wait/store ladder
# baseline (speedup 1.0000x reference)
; #define EPI_LOOP_ROWS  _Pragma("unroll") for (int ai = 0; ai < 2; ++ai) _Pragma("unroll") for (int m = 0; m < 4; ++m)
;     __device__ __forceinline__ void operator()(const Acc& acc, const Unit& u, int wr, int wc, int fr, int fq) const {
;         const int col0 = u.pn * 256 + wc * 32 + 8 * fq;
;         const float* rb = (u.pm < 128) ? resA + (size_t)u.pm * 256 * DM : resB + (size_t)(u.pm - 128) * 256 * DM;
;         float* ob = out + (size_t)u.pm * 256 * DM;
;         EPI_LOOP_ROWS { const size_t off = (size_t)(ai * HALF + wr * 64 + m * 16 + fr) * DM + col0;
; #pragma unroll
;             for (int bj = 0; bj < 2; ++bj) { const f32x4 r0 = *(const f32x4*)(rb + off + bj * HALF), r1 = *(const f32x4*)(rb + off + bj * HALF + 4);
;                 *(f32x4*)(ob + off + bj * HALF) = r0 * ALPHA + acc[ai][bj][m][0]; *(f32x4*)(ob + off + bj * HALF + 4) = r1 * ALPHA + acc[ai][bj][m][1]; } }
;     }
.LBB0_832:
	v_lshl_or_b32 v160, s53, 8, v163
	v_ashrrev_i32_e32 v161, 31, v160
	s_add_u32 s34, s62, s38
	s_addc_u32 s35, s63, s39
	s_andn2_b64 vcc, exec, s[8:9]
	s_mov_b64 s[8:9], -1
	v_lshl_add_u64 v[232:233], v[136:137], 0, v[160:161]
	v_lshlrev_b64 v[232:233], 2, v[232:233]
	v_lshl_add_u64 v[220:221], s[36:37], 0, v[232:233]
	v_lshl_add_u64 v[222:223], s[34:35], 0, v[232:233]
	global_load_dwordx4 v[168:171], v[220:221], off
	global_load_dwordx4 v[172:175], v[220:221], off offset:16
	global_load_dwordx4 v[176:179], v[220:221], off offset:512
	global_load_dwordx4 v[180:183], v[220:221], off offset:528
	v_lshl_add_u64 v[232:233], v[138:139], 0, v[160:161]
	v_lshlrev_b64 v[232:233], 2, v[232:233]
	v_lshl_add_u64 v[224:225], s[36:37], 0, v[232:233]
	v_lshl_add_u64 v[226:227], s[34:35], 0, v[232:233]
	global_load_dwordx4 v[184:187], v[224:225], off
	global_load_dwordx4 v[192:195], v[224:225], off offset:16
	global_load_dwordx4 v[196:199], v[224:225], off offset:512
	global_load_dwordx4 v[200:203], v[224:225], off offset:528
	v_lshl_add_u64 v[232:233], v[140:141], 0, v[160:161]
	v_lshlrev_b64 v[232:233], 2, v[232:233]
	v_lshl_add_u64 v[228:229], s[36:37], 0, v[232:233]
	v_lshl_add_u64 v[230:231], s[34:35], 0, v[232:233]
	global_load_dwordx4 v[204:207], v[228:229], off
	global_load_dwordx4 v[208:211], v[228:229], off offset:16
	global_load_dwordx4 v[212:215], v[228:229], off offset:512
	global_load_dwordx4 v[216:219], v[228:229], off offset:528
	s_waitcnt vmcnt(11)
	v_pk_fma_f32 v[168:169], v[168:169], s[22:23], v[124:125] op_sel_hi:[1,0,1]
	v_pk_fma_f32 v[170:171], v[170:171], s[22:23], v[126:127] op_sel_hi:[1,0,1]
	global_store_dwordx4 v[222:223], v[168:171], off
	s_waitcnt vmcnt(11)
	v_pk_fma_f32 v[172:173], v[172:173], s[22:23], v[120:121] op_sel_hi:[1,0,1]
	v_pk_fma_f32 v[174:175], v[174:175], s[22:23], v[122:123] op_sel_hi:[1,0,1]
	global_store_dwordx4 v[222:223], v[172:175], off offset:16
	s_waitcnt vmcnt(11)
	v_pk_fma_f32 v[176:177], v[176:177], s[22:23], v[112:113] op_sel_hi:[1,0,1]
	v_pk_fma_f32 v[178:179], v[178:179], s[22:23], v[114:115] op_sel_hi:[1,0,1]
	global_store_dwordx4 v[222:223], v[176:179], off offset:512
	s_waitcnt vmcnt(11)
	v_pk_fma_f32 v[180:181], v[180:181], s[22:23], v[104:105] op_sel_hi:[1,0,1]
	v_pk_fma_f32 v[182:183], v[182:183], s[22:23], v[106:107] op_sel_hi:[1,0,1]
	global_store_dwordx4 v[222:223], v[180:183], off offset:528
	s_waitcnt vmcnt(11)
	v_pk_fma_f32 v[184:185], v[184:185], s[22:23], v[116:117] op_sel_hi:[1,0,1]
	v_pk_fma_f32 v[186:187], v[186:187], s[22:23], v[118:119] op_sel_hi:[1,0,1]
	global_store_dwordx4 v[226:227], v[184:187], off
	s_waitcnt vmcnt(11)
	v_pk_fma_f32 v[192:193], v[192:193], s[22:23], v[108:109] op_sel_hi:[1,0,1]
	v_pk_fma_f32 v[194:195], v[194:195], s[22:23], v[110:111] op_sel_hi:[1,0,1]
	global_store_dwordx4 v[226:227], v[192:195], off offset:16
	s_waitcnt vmcnt(11)
	v_pk_fma_f32 v[196:197], v[196:197], s[22:23], v[96:97] op_sel_hi:[1,0,1]
	v_pk_fma_f32 v[198:199], v[198:199], s[22:23], v[98:99] op_sel_hi:[1,0,1]
	global_store_dwordx4 v[226:227], v[196:199], off offset:512
	s_waitcnt vmcnt(11)
	v_pk_fma_f32 v[200:201], v[200:201], s[22:23], v[88:89] op_sel_hi:[1,0,1]
	v_pk_fma_f32 v[202:203], v[202:203], s[22:23], v[90:91] op_sel_hi:[1,0,1]
	global_store_dwordx4 v[226:227], v[200:203], off offset:528
	s_waitcnt vmcnt(11)
	v_pk_fma_f32 v[204:205], v[204:205], s[22:23], v[100:101] op_sel_hi:[1,0,1]
	v_pk_fma_f32 v[206:207], v[206:207], s[22:23], v[102:103] op_sel_hi:[1,0,1]
	global_store_dwordx4 v[230:231], v[204:207], off
	s_waitcnt vmcnt(11)
	v_pk_fma_f32 v[208:209], v[208:209], s[22:23], v[92:93] op_sel_hi:[1,0,1]
	v_pk_fma_f32 v[210:211], v[210:211], s[22:23], v[94:95] op_sel_hi:[1,0,1]
	global_store_dwordx4 v[230:231], v[208:211], off offset:16
	s_waitcnt vmcnt(11)
	v_pk_fma_f32 v[212:213], v[212:213], s[22:23], v[80:81] op_sel_hi:[1,0,1]
	v_pk_fma_f32 v[214:215], v[214:215], s[22:23], v[82:83] op_sel_hi:[1,0,1]
	global_store_dwordx4 v[230:231], v[212:215], off offset:512
	s_waitcnt vmcnt(11)
	v_pk_fma_f32 v[216:217], v[216:217], s[22:23], v[72:73] op_sel_hi:[1,0,1]
	v_pk_fma_f32 v[218:219], v[218:219], s[22:23], v[74:75] op_sel_hi:[1,0,1]
	global_store_dwordx4 v[230:231], v[216:219], off offset:528
	v_lshl_add_u64 v[232:233], v[142:143], 0, v[160:161]
	v_lshlrev_b64 v[232:233], 2, v[232:233]
	v_lshl_add_u64 v[220:221], s[36:37], 0, v[232:233]
	v_lshl_add_u64 v[222:223], s[34:35], 0, v[232:233]
	global_load_dwordx4 v[168:171], v[220:221], off
	global_load_dwordx4 v[172:175], v[220:221], off offset:16
	global_load_dwordx4 v[176:179], v[220:221], off offset:512
	global_load_dwordx4 v[180:183], v[220:221], off offset:528
	v_lshl_add_u64 v[232:233], v[144:145], 0, v[160:161]
	v_lshlrev_b64 v[232:233], 2, v[232:233]
	v_lshl_add_u64 v[224:225], s[36:37], 0, v[232:233]
	v_lshl_add_u64 v[226:227], s[34:35], 0, v[232:233]
	global_load_dwordx4 v[184:187], v[224:225], off
	global_load_dwordx4 v[192:195], v[224:225], off offset:16
	global_load_dwordx4 v[196:199], v[224:225], off offset:512
	global_load_dwordx4 v[200:203], v[224:225], off offset:528
	v_lshl_add_u64 v[232:233], v[146:147], 0, v[160:161]
	v_lshlrev_b64 v[232:233], 2, v[232:233]
	v_lshl_add_u64 v[228:229], s[36:37], 0, v[232:233]
	v_lshl_add_u64 v[230:231], s[34:35], 0, v[232:233]
	global_load_dwordx4 v[204:207], v[228:229], off
	global_load_dwordx4 v[208:211], v[228:229], off offset:16
	global_load_dwordx4 v[212:215], v[228:229], off offset:512
	global_load_dwordx4 v[216:219], v[228:229], off offset:528
	s_waitcnt vmcnt(11)
; #define PG8_BAR __builtin_amdgcn_s_barrier()
; #define EPI_LOOP_ROWS  _Pragma("unroll") for (int ai = 0; ai < 2; ++ai) _Pragma("unroll") for (int m = 0; m < 4; ++m)
; template <class Epi, class Sched, bool F8 = false>
; __device__ __forceinline__ void gemm_phase(LAS unsigned char* lds, const Gemm g, const Sched& S, const Epi& E) {
;     ...
;         cur = nxt; cA = nA; cB = nB; ++ui;
;         if (wr == 1) PG8_BAR;
;     __device__ __forceinline__ void operator()(const Acc& acc, const Unit& u, int wr, int wc, int fr, int fq) const {
;     ...
;         EPI_LOOP_ROWS { const size_t off = (size_t)(ai * HALF + wr * 64 + m * 16 + fr) * DM + col0;
; #pragma unroll
;             for (int bj = 0; bj < 2; ++bj) { const f32x4 r0 = *(const f32x4*)(rb + off + bj * HALF), r1 = *(const f32x4*)(rb + off + bj * HALF + 4);
;                 *(f32x4*)(ob + off + bj * HALF) = r0 * ALPHA + acc[ai][bj][m][0]; *(f32x4*)(ob + off + bj * HALF + 4) = r1 * ALPHA + acc[ai][bj][m][1]; } }
	v_pk_fma_f32 v[168:169], v[168:169], s[22:23], v[84:85] op_sel_hi:[1,0,1]
	v_pk_fma_f32 v[170:171], v[170:171], s[22:23], v[86:87] op_sel_hi:[1,0,1]
	global_store_dwordx4 v[222:223], v[168:171], off
	s_waitcnt vmcnt(11)
	v_pk_fma_f32 v[172:173], v[172:173], s[22:23], v[76:77] op_sel_hi:[1,0,1]
	v_pk_fma_f32 v[174:175], v[174:175], s[22:23], v[78:79] op_sel_hi:[1,0,1]
	global_store_dwordx4 v[222:223], v[172:175], off offset:16
	s_waitcnt vmcnt(11)
	v_pk_fma_f32 v[176:177], v[176:177], s[22:23], v[68:69] op_sel_hi:[1,0,1]
	v_pk_fma_f32 v[178:179], v[178:179], s[22:23], v[70:71] op_sel_hi:[1,0,1]
	global_store_dwordx4 v[222:223], v[176:179], off offset:512
	s_waitcnt vmcnt(11)
	v_pk_fma_f32 v[180:181], v[180:181], s[22:23], v[64:65] op_sel_hi:[1,0,1]
	v_pk_fma_f32 v[182:183], v[182:183], s[22:23], v[66:67] op_sel_hi:[1,0,1]
	global_store_dwordx4 v[222:223], v[180:183], off offset:528
	s_waitcnt vmcnt(11)
	v_pk_fma_f32 v[184:185], v[184:185], s[22:23], v[60:61] op_sel_hi:[1,0,1]
	v_pk_fma_f32 v[186:187], v[186:187], s[22:23], v[62:63] op_sel_hi:[1,0,1]
	global_store_dwordx4 v[226:227], v[184:187], off
	s_waitcnt vmcnt(11)
	v_pk_fma_f32 v[192:193], v[192:193], s[22:23], v[56:57] op_sel_hi:[1,0,1]
	v_pk_fma_f32 v[194:195], v[194:195], s[22:23], v[58:59] op_sel_hi:[1,0,1]
	global_store_dwordx4 v[226:227], v[192:195], off offset:16
	s_waitcnt vmcnt(11)
	v_pk_fma_f32 v[196:197], v[196:197], s[22:23], v[48:49] op_sel_hi:[1,0,1]
	v_pk_fma_f32 v[198:199], v[198:199], s[22:23], v[50:51] op_sel_hi:[1,0,1]
	global_store_dwordx4 v[226:227], v[196:199], off offset:512
	s_waitcnt vmcnt(11)
	v_pk_fma_f32 v[200:201], v[200:201], s[22:23], v[40:41] op_sel_hi:[1,0,1]
	v_pk_fma_f32 v[202:203], v[202:203], s[22:23], v[42:43] op_sel_hi:[1,0,1]
	global_store_dwordx4 v[226:227], v[200:203], off offset:528
	s_waitcnt vmcnt(11)
	v_pk_fma_f32 v[204:205], v[204:205], s[22:23], v[52:53] op_sel_hi:[1,0,1]
	v_pk_fma_f32 v[206:207], v[206:207], s[22:23], v[54:55] op_sel_hi:[1,0,1]
	global_store_dwordx4 v[230:231], v[204:207], off
	s_waitcnt vmcnt(11)
	v_pk_fma_f32 v[208:209], v[208:209], s[22:23], v[44:45] op_sel_hi:[1,0,1]
	v_pk_fma_f32 v[210:211], v[210:211], s[22:23], v[46:47] op_sel_hi:[1,0,1]
	global_store_dwordx4 v[230:231], v[208:211], off offset:16
	s_waitcnt vmcnt(11)
	v_pk_fma_f32 v[212:213], v[212:213], s[22:23], v[32:33] op_sel_hi:[1,0,1]
	v_pk_fma_f32 v[214:215], v[214:215], s[22:23], v[34:35] op_sel_hi:[1,0,1]
	global_store_dwordx4 v[230:231], v[212:215], off offset:512
	s_waitcnt vmcnt(11)
	v_pk_fma_f32 v[216:217], v[216:217], s[22:23], v[24:25] op_sel_hi:[1,0,1]
	v_pk_fma_f32 v[218:219], v[218:219], s[22:23], v[26:27] op_sel_hi:[1,0,1]
	global_store_dwordx4 v[230:231], v[216:219], off offset:528
	v_lshl_add_u64 v[232:233], v[148:149], 0, v[160:161]
	v_lshlrev_b64 v[232:233], 2, v[232:233]
	v_lshl_add_u64 v[220:221], s[36:37], 0, v[232:233]
	v_lshl_add_u64 v[222:223], s[34:35], 0, v[232:233]
	global_load_dwordx4 v[168:171], v[220:221], off
	global_load_dwordx4 v[172:175], v[220:221], off offset:16
	global_load_dwordx4 v[176:179], v[220:221], off offset:512
	global_load_dwordx4 v[180:183], v[220:221], off offset:528
	v_lshl_add_u64 v[232:233], v[150:151], 0, v[160:161]
	v_lshlrev_b64 v[232:233], 2, v[232:233]
	v_lshl_add_u64 v[224:225], s[36:37], 0, v[232:233]
	v_lshl_add_u64 v[226:227], s[34:35], 0, v[232:233]
	global_load_dwordx4 v[184:187], v[224:225], off
	global_load_dwordx4 v[192:195], v[224:225], off offset:16
	global_load_dwordx4 v[196:199], v[224:225], off offset:512
	global_load_dwordx4 v[200:203], v[224:225], off offset:528
	s_waitcnt vmcnt(7)
	v_pk_fma_f32 v[168:169], v[168:169], s[22:23], v[36:37] op_sel_hi:[1,0,1]
	v_pk_fma_f32 v[170:171], v[170:171], s[22:23], v[38:39] op_sel_hi:[1,0,1]
	global_store_dwordx4 v[222:223], v[168:171], off
	s_waitcnt vmcnt(7)
	v_pk_fma_f32 v[172:173], v[172:173], s[22:23], v[28:29] op_sel_hi:[1,0,1]
	v_pk_fma_f32 v[174:175], v[174:175], s[22:23], v[30:31] op_sel_hi:[1,0,1]
	global_store_dwordx4 v[222:223], v[172:175], off offset:16
	s_waitcnt vmcnt(7)
	v_pk_fma_f32 v[176:177], v[176:177], s[22:23], v[16:17] op_sel_hi:[1,0,1]
	v_pk_fma_f32 v[178:179], v[178:179], s[22:23], v[18:19] op_sel_hi:[1,0,1]
	global_store_dwordx4 v[222:223], v[176:179], off offset:512
	s_waitcnt vmcnt(7)
	v_pk_fma_f32 v[180:181], v[180:181], s[22:23], v[8:9] op_sel_hi:[1,0,1]
	v_pk_fma_f32 v[182:183], v[182:183], s[22:23], v[10:11] op_sel_hi:[1,0,1]
	global_store_dwordx4 v[222:223], v[180:183], off offset:528
	s_waitcnt vmcnt(7)
	v_pk_fma_f32 v[184:185], v[184:185], s[22:23], v[20:21] op_sel_hi:[1,0,1]
	v_pk_fma_f32 v[186:187], v[186:187], s[22:23], v[22:23] op_sel_hi:[1,0,1]
	global_store_dwordx4 v[226:227], v[184:187], off
	s_waitcnt vmcnt(7)
	v_pk_fma_f32 v[192:193], v[192:193], s[22:23], v[12:13] op_sel_hi:[1,0,1]
	v_pk_fma_f32 v[194:195], v[194:195], s[22:23], v[14:15] op_sel_hi:[1,0,1]
	global_store_dwordx4 v[226:227], v[192:195], off offset:16
	s_waitcnt vmcnt(7)
	v_pk_fma_f32 v[196:197], v[196:197], s[22:23], v[4:5] op_sel_hi:[1,0,1]
	v_pk_fma_f32 v[198:199], v[198:199], s[22:23], v[6:7] op_sel_hi:[1,0,1]
	global_store_dwordx4 v[226:227], v[196:199], off offset:512
	s_waitcnt vmcnt(7)
	v_pk_fma_f32 v[200:201], v[200:201], s[22:23], v[0:1] op_sel_hi:[1,0,1]
	v_pk_fma_f32 v[202:203], v[202:203], s[22:23], v[2:3] op_sel_hi:[1,0,1]
	global_store_dwordx4 v[226:227], v[200:203], off offset:528
	s_cbranch_vccnz .LBB0_821
	s_andn2_b64 vcc, exec, s[16:17]
	s_cbranch_vccnz .LBB0_820
	s_barrier
	s_branch .LBB0_820
